# v60 plus diff-attention item start: the first wait+barrier moved below the register-only setup (slope, accumulator zeroing), docs 7.2
# speedup vs baseline: 1.0032x; 1.0032x over previous
; __device__ __forceinline__ void wait_all_barrier() { asm volatile("s_waitcnt vmcnt(0) lgkmcnt(0)\n\ts_barrier" ::: "memory"); }
; #define LOAD_PAIR(stage, s0) do { _Pragma("unroll") for (int i_ = 0; i_ < 4; ++i_) { const bf16* src_ = kvsrc[i_] + (size_t)(s0) * INW; \
;         dma16(src_, lds + (stage) + pofs[i_]); dma16(src_ + 768, lds + (stage) + 32768 + pofs[i_]); } } while (0)
; __device__ __forceinline__ int diff_item(ldsp lds, int qt, int bh, bool pre, unsigned* nctr, const bf16* U, bf16* O, const float* subw, float lam, float omlinit, float M0, int wave, int lane) {
;     ...
;     f32x16 o[4];
; #pragma unroll
;     for (int et = 0; et < 4; ++et)
; #pragma unroll
;         for (int i = 0; i < 16; ++i) o[et][i] = 0.f;
;     float lsum = 0.f;
;     const float nslope2 = -exp2f(-8.0f * (float)(h + 1) / 6.0f) * LOG2E;
;     const int jmax = 2 * qt + (wq >> 1);
;     const unsigned lds0 = (unsigned)(size_t)lds; LaneAddr LA; lane_addr<4>(LA, 8 * c, 0, lane);
;     const int prow = lane >> 4, chp = lane & 15;
;     const bf16* kvsrc[4]; int pofs[4];
; #pragma unroll
;     for (int i = 0; i < 4; ++i) { const int pi = wave * 4 + i, row = 4 * pi + prow; const unsigned ch = (unsigned)chp ^ (((unsigned)prow << 2) | ((unsigned)pi & 3u));
;         kvsrc[i] = U + (tokbase + row) * INW + 768 + h * 128 + ch * 8; pofs[i] = 1024 * pi; }
;     ...
;     if (!pre) LOAD_PAIR(0, 0);
;     wait_all_barrier();
;     for (int p = 0; p < qt; ++p) {
.LBB0_807:
	s_add_i32 s73, s73, 1
	v_cvt_f32_i32_e32 v0, s73
	v_mov_b32_e32 v15, 0
	v_mov_b32_e32 v14, v15
	v_mul_f32_e32 v0, 0xc1000000, v0
	v_div_scale_f32 v1, s[14:15], s30, s30, v0
	v_rcp_f32_e32 v2, v1
	v_div_scale_f32 v3, vcc, v0, s30, v0
	s_mov_b32 s14, 0xc2fc0000
	v_fma_f32 v4, -v1, v2, 1.0
	v_fmac_f32_e32 v2, v4, v2
	v_mul_f32_e32 v4, v3, v2
	v_fma_f32 v5, -v1, v4, v3
	v_fmac_f32_e32 v4, v5, v2
	v_fma_f32 v1, -v1, v4, v3
	v_div_fmas_f32 v1, v1, v2, v4
	v_div_fixup_f32 v0, v1, s30, v0
	v_cmp_gt_f32_e32 vcc, s14, v0
	s_and_b64 s[14:15], vcc, exec
	s_cselect_b32 s14, 0xffffffc0, 0
	v_cndmask_b32_e32 v1, 0, v212, vcc
	v_add_f32_e32 v0, v0, v1
	v_exp_f32_e32 v0, v0
	s_cmp_eq_u32 s80, 0
	v_mov_b32_e32 v13, v15
	v_mov_b32_e32 v12, v15
	v_ldexp_f32 v0, v0, s14
	v_mul_f32_e32 v200, 0xbfb8aa3b, v0
	v_mov_b32_e32 v11, v15
	v_mov_b32_e32 v10, v15
	v_mov_b32_e32 v9, v15
	v_mov_b32_e32 v8, v15
	v_mov_b32_e32 v7, v15
	v_mov_b32_e32 v6, v15
	v_mov_b32_e32 v5, v15
	v_mov_b32_e32 v4, v15
	v_mov_b32_e32 v3, v15
	v_mov_b32_e32 v2, v15
	v_mov_b32_e32 v1, v15
	v_mov_b32_e32 v0, v15
	v_mov_b32_e32 v31, v15
	v_mov_b32_e32 v30, v15
	v_mov_b32_e32 v29, v15
	v_mov_b32_e32 v28, v15
	v_mov_b32_e32 v27, v15
	v_mov_b32_e32 v26, v15
	v_mov_b32_e32 v25, v15
	v_mov_b32_e32 v24, v15
	v_mov_b32_e32 v23, v15
	v_mov_b32_e32 v22, v15
	v_mov_b32_e32 v21, v15
	v_mov_b32_e32 v20, v15
	v_mov_b32_e32 v19, v15
	v_mov_b32_e32 v18, v15
	v_mov_b32_e32 v17, v15
	v_mov_b32_e32 v16, v15
	v_mov_b32_e32 v47, v15
	v_mov_b32_e32 v46, v15
	v_mov_b32_e32 v45, v15
	v_mov_b32_e32 v44, v15
	v_mov_b32_e32 v43, v15
	v_mov_b32_e32 v42, v15
	v_mov_b32_e32 v41, v15
	v_mov_b32_e32 v40, v15
	v_mov_b32_e32 v39, v15
	v_mov_b32_e32 v38, v15
	v_mov_b32_e32 v37, v15
	v_mov_b32_e32 v36, v15
	v_mov_b32_e32 v35, v15
	v_mov_b32_e32 v34, v15
	v_mov_b32_e32 v33, v15
	v_mov_b32_e32 v32, v15
	v_mov_b32_e32 v63, v15
	v_mov_b32_e32 v62, v15
	v_mov_b32_e32 v61, v15
	v_mov_b32_e32 v60, v15
	v_mov_b32_e32 v59, v15
	v_mov_b32_e32 v58, v15
	v_mov_b32_e32 v57, v15
	v_mov_b32_e32 v56, v15
	v_mov_b32_e32 v55, v15
	v_mov_b32_e32 v54, v15
	v_mov_b32_e32 v53, v15
	v_mov_b32_e32 v52, v15
	v_mov_b32_e32 v51, v15
	v_mov_b32_e32 v50, v15
	v_mov_b32_e32 v49, v15
	v_mov_b32_e32 v48, v15
	v_mov_b32_e32 v195, v15
	s_waitcnt vmcnt(0) lgkmcnt(0)
	s_barrier
	s_cbranch_scc1 .LBB0_810
	v_mov_b32_e32 v195, 0
	v_lshl_add_u32 v193, s72, 7, v208
	s_mov_b32 s24, 0x10000
	s_movk_i32 s70, 0x80
	s_mov_b32 s71, s80
	v_mov_b32_e32 v0, 0
	v_mov_b32_e32 v1, v195
	v_mov_b32_e32 v2, v195
	v_mov_b32_e32 v3, v195
	v_mov_b32_e32 v4, v195
	v_mov_b32_e32 v5, v195
	v_mov_b32_e32 v6, v195
	v_mov_b32_e32 v7, v195
	v_mov_b32_e32 v8, v195
	v_mov_b32_e32 v9, v195
	v_mov_b32_e32 v10, v195
	v_mov_b32_e32 v11, v195
	v_mov_b32_e32 v12, v195
	v_mov_b32_e32 v13, v195
	v_mov_b32_e32 v14, v195
	v_mov_b32_e32 v15, v195
	v_mov_b32_e32 v16, 0
	v_mov_b32_e32 v17, v195
	v_mov_b32_e32 v18, v195
	v_mov_b32_e32 v19, v195
	v_mov_b32_e32 v20, v195
	v_mov_b32_e32 v21, v195
	v_mov_b32_e32 v22, v195
	v_mov_b32_e32 v23, v195
	v_mov_b32_e32 v24, v195
	v_mov_b32_e32 v25, v195
	v_mov_b32_e32 v26, v195
	v_mov_b32_e32 v27, v195
	v_mov_b32_e32 v28, v195
	v_mov_b32_e32 v29, v195
	v_mov_b32_e32 v30, v195
	v_mov_b32_e32 v31, v195
	v_mov_b32_e32 v32, 0
	v_mov_b32_e32 v33, v195
	v_mov_b32_e32 v34, v195
	v_mov_b32_e32 v35, v195
	v_mov_b32_e32 v36, v195
	v_mov_b32_e32 v37, v195
	v_mov_b32_e32 v38, v195
	v_mov_b32_e32 v39, v195
	v_mov_b32_e32 v40, v195
	v_mov_b32_e32 v41, v195
	v_mov_b32_e32 v42, v195
	v_mov_b32_e32 v43, v195
	v_mov_b32_e32 v44, v195
	v_mov_b32_e32 v45, v195
	v_mov_b32_e32 v46, v195
	v_mov_b32_e32 v47, v195
	v_mov_b32_e32 v48, 0
	v_mov_b32_e32 v49, v195
	v_mov_b32_e32 v50, v195
	v_mov_b32_e32 v51, v195
	v_mov_b32_e32 v52, v195
	v_mov_b32_e32 v53, v195
	v_mov_b32_e32 v54, v195
	v_mov_b32_e32 v55, v195
	v_mov_b32_e32 v56, v195
	v_mov_b32_e32 v57, v195
	v_mov_b32_e32 v58, v195
	v_mov_b32_e32 v59, v195
	v_mov_b32_e32 v60, v195
	v_mov_b32_e32 v61, v195
	v_mov_b32_e32 v62, v195
	v_mov_b32_e32 v63, v195

; __device__ __forceinline__ void wait_all_barrier() { asm volatile("s_waitcnt vmcnt(0) lgkmcnt(0)\n\ts_barrier" ::: "memory"); }
; #define LOAD_PAIR(stage, s0) do { _Pragma("unroll") for (int i_ = 0; i_ < 4; ++i_) { const bf16* src_ = kvsrc[i_] + (size_t)(s0) * INW; \
;         dma16(src_, lds + (stage) + pofs[i_]); dma16(src_ + 768, lds + (stage) + 32768 + pofs[i_]); } } while (0)
; __device__ __forceinline__ int diff_item(ldsp lds, int qt, int bh, bool pre, unsigned* nctr, const bf16* U, bf16* O, const float* subw, float lam, float omlinit, float M0, int wave, int lane) {
;     ...
;     f32x16 o[4];
; #pragma unroll
;     for (int et = 0; et < 4; ++et)
; #pragma unroll
;         for (int i = 0; i < 16; ++i) o[et][i] = 0.f;
;     float lsum = 0.f;
;     const float nslope2 = -exp2f(-8.0f * (float)(h + 1) / 6.0f) * LOG2E;
;     const int jmax = 2 * qt + (wq >> 1);
;     const unsigned lds0 = (unsigned)(size_t)lds; LaneAddr LA; lane_addr<4>(LA, 8 * c, 0, lane);
;     const int prow = lane >> 4, chp = lane & 15;
;     const bf16* kvsrc[4]; int pofs[4];
; #pragma unroll
;     for (int i = 0; i < 4; ++i) { const int pi = wave * 4 + i, row = 4 * pi + prow; const unsigned ch = (unsigned)chp ^ (((unsigned)prow << 2) | ((unsigned)pi & 3u));
;         kvsrc[i] = U + (tokbase + row) * INW + 768 + h * 128 + ch * 8; pofs[i] = 1024 * pi; }
;     ...
;     if (!pre) LOAD_PAIR(0, 0);
;     wait_all_barrier();
;     for (int p = 0; p < qt; ++p) {
.LBB0_1851:
	s_add_i32 s67, s67, 1
	v_cvt_f32_i32_e32 v0, s67
	v_mov_b32_e32 v15, 0
	v_mov_b32_e32 v14, v15
	v_mul_f32_e32 v0, 0xc1000000, v0
	v_div_scale_f32 v1, s[4:5], s72, s72, v0
	v_rcp_f32_e32 v2, v1
	v_div_scale_f32 v3, vcc, v0, s72, v0
	s_mov_b32 s4, 0xc2fc0000
	v_fma_f32 v4, -v1, v2, 1.0
	v_fmac_f32_e32 v2, v4, v2
	v_mul_f32_e32 v4, v3, v2
	v_fma_f32 v5, -v1, v4, v3
	v_fmac_f32_e32 v4, v5, v2
	v_fma_f32 v1, -v1, v4, v3
	v_div_fmas_f32 v1, v1, v2, v4
	v_div_fixup_f32 v0, v1, s72, v0
	v_cmp_gt_f32_e32 vcc, s4, v0
	s_and_b64 s[4:5], vcc, exec
	s_cselect_b32 s4, 0xffffffc0, 0
	v_cndmask_b32_e32 v1, 0, v212, vcc
	v_add_f32_e32 v0, v0, v1
	v_exp_f32_e32 v0, v0
	s_cmp_eq_u32 s76, 0
	v_mov_b32_e32 v13, v15
	v_mov_b32_e32 v12, v15
	v_ldexp_f32 v0, v0, s4
	v_mul_f32_e32 v200, 0xbfb8aa3b, v0
	v_mov_b32_e32 v11, v15
	v_mov_b32_e32 v10, v15
	v_mov_b32_e32 v9, v15
	v_mov_b32_e32 v8, v15
	v_mov_b32_e32 v7, v15
	v_mov_b32_e32 v6, v15
	v_mov_b32_e32 v5, v15
	v_mov_b32_e32 v4, v15
	v_mov_b32_e32 v3, v15
	v_mov_b32_e32 v2, v15
	v_mov_b32_e32 v1, v15
	v_mov_b32_e32 v0, v15
	v_mov_b32_e32 v31, v15
	v_mov_b32_e32 v30, v15
	v_mov_b32_e32 v29, v15
	v_mov_b32_e32 v28, v15
	v_mov_b32_e32 v27, v15
	v_mov_b32_e32 v26, v15
	v_mov_b32_e32 v25, v15
	v_mov_b32_e32 v24, v15
	v_mov_b32_e32 v23, v15
	v_mov_b32_e32 v22, v15
	v_mov_b32_e32 v21, v15
	v_mov_b32_e32 v20, v15
	v_mov_b32_e32 v19, v15
	v_mov_b32_e32 v18, v15
	v_mov_b32_e32 v17, v15
	v_mov_b32_e32 v16, v15
	v_mov_b32_e32 v47, v15
	v_mov_b32_e32 v46, v15
	v_mov_b32_e32 v45, v15
	v_mov_b32_e32 v44, v15
	v_mov_b32_e32 v43, v15
	v_mov_b32_e32 v42, v15
	v_mov_b32_e32 v41, v15
	v_mov_b32_e32 v40, v15
	v_mov_b32_e32 v39, v15
	v_mov_b32_e32 v38, v15
	v_mov_b32_e32 v37, v15
	v_mov_b32_e32 v36, v15
	v_mov_b32_e32 v35, v15
	v_mov_b32_e32 v34, v15
	v_mov_b32_e32 v33, v15
	v_mov_b32_e32 v32, v15
	v_mov_b32_e32 v63, v15
	v_mov_b32_e32 v62, v15
	v_mov_b32_e32 v61, v15
	v_mov_b32_e32 v60, v15
	v_mov_b32_e32 v59, v15
	v_mov_b32_e32 v58, v15
	v_mov_b32_e32 v57, v15
	v_mov_b32_e32 v56, v15
	v_mov_b32_e32 v55, v15
	v_mov_b32_e32 v54, v15
	v_mov_b32_e32 v53, v15
	v_mov_b32_e32 v52, v15
	v_mov_b32_e32 v51, v15
	v_mov_b32_e32 v50, v15
	v_mov_b32_e32 v49, v15
	v_mov_b32_e32 v48, v15
	v_mov_b32_e32 v195, v15
	s_waitcnt vmcnt(0) lgkmcnt(0)
	s_barrier
	s_cbranch_scc1 .LBB0_1854
	v_mov_b32_e32 v195, 0
	v_lshl_add_u32 v193, s66, 7, v208
	s_mov_b32 s22, 0x10000
	s_movk_i32 s64, 0x80
	s_mov_b32 s65, s76
	v_mov_b32_e32 v0, 0
	v_mov_b32_e32 v1, v195
	v_mov_b32_e32 v2, v195
	v_mov_b32_e32 v3, v195
	v_mov_b32_e32 v4, v195
	v_mov_b32_e32 v5, v195
	v_mov_b32_e32 v6, v195
	v_mov_b32_e32 v7, v195
	v_mov_b32_e32 v8, v195
	v_mov_b32_e32 v9, v195
	v_mov_b32_e32 v10, v195
	v_mov_b32_e32 v11, v195
	v_mov_b32_e32 v12, v195
	v_mov_b32_e32 v13, v195
	v_mov_b32_e32 v14, v195
	v_mov_b32_e32 v15, v195
	v_mov_b32_e32 v16, 0
	v_mov_b32_e32 v17, v195
	v_mov_b32_e32 v18, v195
	v_mov_b32_e32 v19, v195
	v_mov_b32_e32 v20, v195
	v_mov_b32_e32 v21, v195
	v_mov_b32_e32 v22, v195
	v_mov_b32_e32 v23, v195
	v_mov_b32_e32 v24, v195
	v_mov_b32_e32 v25, v195
	v_mov_b32_e32 v26, v195
	v_mov_b32_e32 v27, v195
	v_mov_b32_e32 v28, v195
	v_mov_b32_e32 v29, v195
	v_mov_b32_e32 v30, v195
	v_mov_b32_e32 v31, v195
	v_mov_b32_e32 v32, 0
	v_mov_b32_e32 v33, v195
	v_mov_b32_e32 v34, v195
	v_mov_b32_e32 v35, v195
	v_mov_b32_e32 v36, v195
	v_mov_b32_e32 v37, v195
	v_mov_b32_e32 v38, v195
	v_mov_b32_e32 v39, v195
	v_mov_b32_e32 v40, v195
	v_mov_b32_e32 v41, v195
	v_mov_b32_e32 v42, v195
	v_mov_b32_e32 v43, v195
	v_mov_b32_e32 v44, v195
	v_mov_b32_e32 v45, v195
	v_mov_b32_e32 v46, v195
	v_mov_b32_e32 v47, v195
	v_mov_b32_e32 v48, 0
	v_mov_b32_e32 v49, v195
	v_mov_b32_e32 v50, v195
	v_mov_b32_e32 v51, v195
	v_mov_b32_e32 v52, v195
	v_mov_b32_e32 v53, v195
	v_mov_b32_e32 v54, v195
	v_mov_b32_e32 v55, v195
	v_mov_b32_e32 v56, v195
	v_mov_b32_e32 v57, v195
	v_mov_b32_e32 v58, v195
	v_mov_b32_e32 v59, v195
	v_mov_b32_e32 v60, v195
	v_mov_b32_e32 v61, v195
	v_mov_b32_e32 v62, v195
	v_mov_b32_e32 v63, v195
